# attention: keys 0-31 of sub-tile A first, their exps under the MFMAs of keys 32-63, those under B's first six, A's row sums (scalar adds) under B's last six
# speedup vs baseline: 1.0125x; 1.0016x over previous
; __device__ __forceinline__ float max3f(float a, float b, float c) { return fmaxf(fmaxf(a, b), c); }
; __device__ __forceinline__ void attn_qk(f32x16& p0, f32x16& p1, const bf16x8 (&kf)[12], const bf16x8 (&qf)[6]) {
;     const f32x16 zero = {0.f, 0.f, 0.f, 0.f, 0.f, 0.f, 0.f, 0.f, 0.f, 0.f, 0.f, 0.f, 0.f, 0.f, 0.f, 0.f};
; #pragma unroll
;     for (int ks = 0; ks < 6; ++ks) {
;         p0 = __builtin_amdgcn_mfma_f32_32x32x16_bf16(kf[2 * ks], qf[ks], ks == 0 ? zero : p0, 0, 0, 0);
;         p1 = __builtin_amdgcn_mfma_f32_32x32x16_bf16(kf[2 * ks + 1], qf[ks], ks == 0 ? zero : p1, 0, 0, 0);
;     }
; }
; __device__ __forceinline__ void attn_softmax(f32x16& p0, f32x16& p1, bf16x8 (&pb)[4], f32x16& o0, f32x16& o1, float& m_run, float& l_run) {
;     float mx = max3f(p0[0], p0[1], p1[0]), my = max3f(p0[2], p0[3], p1[1]);
;     mx = max3f(mx, p1[2], p1[3]);
; #pragma unroll
;     for (int r = 4; r < 16; r += 4) { mx = max3f(mx, p0[r], p0[r + 1]); my = max3f(my, p0[r + 2], p0[r + 3]); mx = max3f(mx, p1[r], p1[r + 1]); my = max3f(my, p1[r + 2], p1[r + 3]); }
;     mx = fmaxf(mx, my);
;     { auto rr = __builtin_amdgcn_permlane32_swap(__float_as_uint(mx), __float_as_uint(mx), false, false); mx = fmaxf(__uint_as_float(rr[0]), __uint_as_float(rr[1])); }
;     const float m_new = fmaxf(m_run, mx);
;     const float alpha = __builtin_amdgcn_exp2f(m_run - m_new);
;     m_run = m_new;
;     p0 = p0 - m_new; p1 = p1 - m_new;
; #pragma unroll
;     for (int r = 0; r < 16; ++r) { p0[r] = __builtin_amdgcn_exp2f(p0[r]); p1[r] = __builtin_amdgcn_exp2f(p1[r]); }
;     f32x16 sm = p0 + p1;
;     f32x2v s2 = (f32x2v){sm[0], sm[1]} + (f32x2v){sm[2], sm[3]};
; #pragma unroll
;     for (int r = 4; r < 16; r += 2) s2 += (f32x2v){sm[r], sm[r + 1]};
;     l_run = l_run * alpha + (s2[0] + s2[1]);
.Lat_both:
	v_add_u32_e32 v1, s37, v222
	v_add_u32_e32 v225, s37, v223
	ds_read_b128 v[138:141], v1
	ds_read_b128 v[142:145], v1 offset:32
	ds_read_b128 v[146:149], v1 offset:64
	ds_read_b128 v[150:153], v1 offset:96
	ds_read_b128 v[154:157], v1 offset:128
	ds_read_b128 v[158:161], v1 offset:160
	ds_read_b128 v[162:165], v1 offset:6656
	ds_read_b128 v[166:169], v1 offset:6688
	s_waitcnt vmcnt(5)
	s_waitcnt lgkmcnt(7)
	v_mfma_f32_32x32x16_bf16 v[34:49], v[138:141], v[114:117], v[98:113]
	ds_read_b128 v[138:141], v1 offset:6720
	s_waitcnt lgkmcnt(7)
	v_mfma_f32_32x32x16_bf16 v[34:49], v[142:145], v[118:121], v[34:49]
	ds_read_b128 v[142:145], v1 offset:6752
	s_waitcnt lgkmcnt(7)
	v_mfma_f32_32x32x16_bf16 v[34:49], v[146:149], v[122:125], v[34:49]
	ds_read_b128 v[146:149], v1 offset:6784
	s_waitcnt lgkmcnt(7)
	v_mfma_f32_32x32x16_bf16 v[34:49], v[150:153], v[126:129], v[34:49]
	ds_read_b128 v[150:153], v1 offset:6816
	s_waitcnt lgkmcnt(7)
	v_mfma_f32_32x32x16_bf16 v[34:49], v[154:157], v[130:133], v[34:49]
	ds_read_b128 v[154:157], v1 offset:13312
	s_waitcnt lgkmcnt(7)
	v_mfma_f32_32x32x16_bf16 v[34:49], v[158:161], v[134:137], v[34:49]
	ds_read_b128 v[158:161], v1 offset:19968
	s_cmp_lg_u32 s7, 0
	s_cbranch_scc1 .Lat_plain_A2
	s_waitcnt lgkmcnt(7)
	v_mfma_f32_32x32x16_bf16 v[50:65], v[162:165], v[114:117], v[98:113]
	ds_read_b128 v[162:165], v1 offset:13344
	s_waitcnt lgkmcnt(7)
	v_mfma_f32_32x32x16_bf16 v[50:65], v[166:169], v[118:121], v[50:65]
	ds_read_b128 v[166:169], v1 offset:20000
	s_nop 2
	v_exp_f32_e32 v34, v34
	v_exp_f32_e32 v35, v35
	v_exp_f32_e32 v36, v36
	v_exp_f32_e32 v37, v37
	s_waitcnt lgkmcnt(7)
	v_mfma_f32_32x32x16_bf16 v[50:65], v[138:141], v[122:125], v[50:65]
	ds_read_b128 v[138:141], v1 offset:13376
	v_exp_f32_e32 v38, v38
	v_exp_f32_e32 v39, v39
	v_exp_f32_e32 v40, v40
	s_waitcnt lgkmcnt(7)
	v_mfma_f32_32x32x16_bf16 v[50:65], v[142:145], v[126:129], v[50:65]
	ds_read_b128 v[142:145], v1 offset:20032
	v_exp_f32_e32 v41, v41
	v_exp_f32_e32 v42, v42
	v_exp_f32_e32 v43, v43
	s_waitcnt lgkmcnt(7)
	v_mfma_f32_32x32x16_bf16 v[50:65], v[146:149], v[130:133], v[50:65]
	ds_read_b128 v[146:149], v1 offset:13408
	v_exp_f32_e32 v44, v44
	v_exp_f32_e32 v45, v45
	v_exp_f32_e32 v46, v46
	s_waitcnt lgkmcnt(7)
	v_mfma_f32_32x32x16_bf16 v[50:65], v[150:153], v[134:137], v[50:65]
	ds_read_b128 v[150:153], v1 offset:20064
	v_exp_f32_e32 v47, v47
	v_exp_f32_e32 v48, v48
	v_exp_f32_e32 v49, v49
	s_waitcnt lgkmcnt(7)
	v_mfma_f32_32x32x16_bf16 v[66:81], v[154:157], v[114:117], v[98:113]
	ds_read_b128 v[154:157], v1 offset:13440
	s_waitcnt lgkmcnt(7)
	v_mfma_f32_32x32x16_bf16 v[82:97], v[158:161], v[114:117], v[98:113]
	ds_read_b128 v[158:161], v1 offset:20096
	s_nop 1
	v_exp_f32_e32 v50, v50
	v_exp_f32_e32 v51, v51
	v_exp_f32_e32 v52, v52
	v_exp_f32_e32 v53, v53
	s_waitcnt lgkmcnt(7)
	v_mfma_f32_32x32x16_bf16 v[66:81], v[162:165], v[118:121], v[66:81]
	ds_read_b128 v[162:165], v1 offset:13472
	v_exp_f32_e32 v54, v54
	v_exp_f32_e32 v55, v55
	v_exp_f32_e32 v56, v56
	s_waitcnt lgkmcnt(7)
	v_mfma_f32_32x32x16_bf16 v[82:97], v[166:169], v[118:121], v[82:97]
	ds_read_b128 v[166:169], v1 offset:20128
	v_exp_f32_e32 v57, v57
	v_exp_f32_e32 v58, v58
	v_exp_f32_e32 v59, v59
	s_waitcnt lgkmcnt(7)
	v_mfma_f32_32x32x16_bf16 v[66:81], v[138:141], v[122:125], v[66:81]
	ds_read_b128 v[170:173], v225 offset:26624
	v_exp_f32_e32 v60, v60
	v_exp_f32_e32 v61, v61
	v_exp_f32_e32 v62, v62
	s_waitcnt lgkmcnt(7)
	v_mfma_f32_32x32x16_bf16 v[82:97], v[142:145], v[122:125], v[82:97]
	ds_read_b128 v[174:177], v225 offset:35328
	v_exp_f32_e32 v63, v63
	v_exp_f32_e32 v64, v64
	v_exp_f32_e32 v65, v65
	s_waitcnt lgkmcnt(7)
	v_mfma_f32_32x32x16_bf16 v[66:81], v[146:149], v[126:129], v[66:81]
	ds_read_b128 v[178:181], v225 offset:26656
	v_add_f32_e32 v250, v34, v36
	v_add_f32_e32 v251, v35, v37
	v_add_f32_e32 v252, v50, v52
	v_add_f32_e32 v253, v51, v53
	v_add_f32_e32 v250, v250, v38
	v_add_f32_e32 v251, v251, v39
	s_waitcnt lgkmcnt(7)
	v_mfma_f32_32x32x16_bf16 v[82:97], v[150:153], v[126:129], v[82:97]
	ds_read_b128 v[182:185], v225 offset:35360
	v_add_f32_e32 v252, v252, v54
	v_add_f32_e32 v253, v253, v55
	v_add_f32_e32 v250, v250, v40
	v_add_f32_e32 v251, v251, v41
	v_add_f32_e32 v252, v252, v56
	s_waitcnt lgkmcnt(7)
	v_mfma_f32_32x32x16_bf16 v[66:81], v[154:157], v[130:133], v[66:81]
	ds_read_b128 v[186:189], v225 offset:26688
	v_add_f32_e32 v253, v253, v57
	v_add_f32_e32 v250, v250, v42
	v_add_f32_e32 v251, v251, v43
	v_add_f32_e32 v252, v252, v58
	v_add_f32_e32 v253, v253, v59
	s_waitcnt lgkmcnt(7)
	v_mfma_f32_32x32x16_bf16 v[82:97], v[158:161], v[130:133], v[82:97]
	ds_read_b128 v[190:193], v225 offset:35392
	v_add_f32_e32 v250, v250, v44
	v_add_f32_e32 v251, v251, v45
	v_add_f32_e32 v252, v252, v60
	v_add_f32_e32 v253, v253, v61
	v_add_f32_e32 v250, v250, v46
	s_waitcnt lgkmcnt(7)
	v_mfma_f32_32x32x16_bf16 v[66:81], v[162:165], v[134:137], v[66:81]
	v_add_f32_e32 v251, v251, v47
	v_add_f32_e32 v252, v252, v62
	v_add_f32_e32 v253, v253, v63
	v_add_f32_e32 v250, v250, v48
	v_add_f32_e32 v251, v251, v49
	s_waitcnt lgkmcnt(6)
	v_mfma_f32_32x32x16_bf16 v[82:97], v[166:169], v[134:137], v[82:97]
	v_add_f32_e32 v252, v252, v64
	v_add_f32_e32 v253, v253, v65
	v_add_f32_e32 v250, v250, v252
	v_add_f32_e32 v251, v251, v253
	v_add_f32_e32 v1, v250, v251
	s_mov_b32 s41, 0
	s_branch .Lat_sum_A2
; __device__ __forceinline__ float max3f(float a, float b, float c) { return fmaxf(fmaxf(a, b), c); }
; __device__ __forceinline__ void attn_qk(f32x16& p0, f32x16& p1, const bf16x8 (&kf)[12], const bf16x8 (&qf)[6]) {
;     const f32x16 zero = {0.f, 0.f, 0.f, 0.f, 0.f, 0.f, 0.f, 0.f, 0.f, 0.f, 0.f, 0.f, 0.f, 0.f, 0.f, 0.f};
; #pragma unroll
;     for (int ks = 0; ks < 6; ++ks) {
;         p0 = __builtin_amdgcn_mfma_f32_32x32x16_bf16(kf[2 * ks], qf[ks], ks == 0 ? zero : p0, 0, 0, 0);
;         p1 = __builtin_amdgcn_mfma_f32_32x32x16_bf16(kf[2 * ks + 1], qf[ks], ks == 0 ? zero : p1, 0, 0, 0);
;     }
; }
; __device__ __forceinline__ void attn_softmax(f32x16& p0, f32x16& p1, bf16x8 (&pb)[4], f32x16& o0, f32x16& o1, float& m_run, float& l_run) {
;     float mx = max3f(p0[0], p0[1], p1[0]), my = max3f(p0[2], p0[3], p1[1]);
;     mx = max3f(mx, p1[2], p1[3]);
; #pragma unroll
;     for (int r = 4; r < 16; r += 4) { mx = max3f(mx, p0[r], p0[r + 1]); my = max3f(my, p0[r + 2], p0[r + 3]); mx = max3f(mx, p1[r], p1[r + 1]); my = max3f(my, p1[r + 2], p1[r + 3]); }
;     mx = fmaxf(mx, my);
;     { auto rr = __builtin_amdgcn_permlane32_swap(__float_as_uint(mx), __float_as_uint(mx), false, false); mx = fmaxf(__uint_as_float(rr[0]), __uint_as_float(rr[1])); }
;     const float m_new = fmaxf(m_run, mx);
;     const float alpha = __builtin_amdgcn_exp2f(m_run - m_new);
;     m_run = m_new;
;     p0 = p0 - m_new; p1 = p1 - m_new;
; #pragma unroll
;     for (int r = 0; r < 16; ++r) { p0[r] = __builtin_amdgcn_exp2f(p0[r]); p1[r] = __builtin_amdgcn_exp2f(p1[r]); }
;     f32x16 sm = p0 + p1;
;     f32x2v s2 = (f32x2v){sm[0], sm[1]} + (f32x2v){sm[2], sm[3]};
; #pragma unroll
;     for (int r = 4; r < 16; r += 2) s2 += (f32x2v){sm[r], sm[r + 1]};
;     l_run = l_run * alpha + (s2[0] + s2[1]);
.Lat_plain_A2:
	s_waitcnt lgkmcnt(7)
	v_mfma_f32_32x32x16_bf16 v[50:65], v[162:165], v[114:117], v[98:113]
	ds_read_b128 v[162:165], v1 offset:13344
	s_waitcnt lgkmcnt(7)
	v_mfma_f32_32x32x16_bf16 v[50:65], v[166:169], v[118:121], v[50:65]
	ds_read_b128 v[166:169], v1 offset:20000
	s_waitcnt lgkmcnt(7)
	v_mfma_f32_32x32x16_bf16 v[50:65], v[138:141], v[122:125], v[50:65]
	ds_read_b128 v[138:141], v1 offset:13376
	s_waitcnt lgkmcnt(7)
	v_mfma_f32_32x32x16_bf16 v[50:65], v[142:145], v[126:129], v[50:65]
	ds_read_b128 v[142:145], v1 offset:20032
	s_waitcnt lgkmcnt(7)
	v_mfma_f32_32x32x16_bf16 v[50:65], v[146:149], v[130:133], v[50:65]
	ds_read_b128 v[146:149], v1 offset:13408
	s_waitcnt lgkmcnt(7)
	v_mfma_f32_32x32x16_bf16 v[50:65], v[150:153], v[134:137], v[50:65]
	ds_read_b128 v[150:153], v1 offset:20064
	s_waitcnt lgkmcnt(7)
	v_mfma_f32_32x32x16_bf16 v[66:81], v[154:157], v[114:117], v[98:113]
	ds_read_b128 v[154:157], v1 offset:13440
	s_waitcnt lgkmcnt(7)
	v_mfma_f32_32x32x16_bf16 v[82:97], v[158:161], v[114:117], v[98:113]
	ds_read_b128 v[158:161], v1 offset:20096
	s_waitcnt lgkmcnt(7)
	v_mfma_f32_32x32x16_bf16 v[66:81], v[162:165], v[118:121], v[66:81]
	ds_read_b128 v[162:165], v1 offset:13472
	s_waitcnt lgkmcnt(7)
	v_mfma_f32_32x32x16_bf16 v[82:97], v[166:169], v[118:121], v[82:97]
	ds_read_b128 v[166:169], v1 offset:20128
	s_waitcnt lgkmcnt(7)
	v_mfma_f32_32x32x16_bf16 v[66:81], v[138:141], v[122:125], v[66:81]
	ds_read_b128 v[170:173], v225 offset:26624
	s_waitcnt lgkmcnt(7)
	v_mfma_f32_32x32x16_bf16 v[82:97], v[142:145], v[122:125], v[82:97]
	ds_read_b128 v[174:177], v225 offset:35328
	s_waitcnt lgkmcnt(7)
	v_mfma_f32_32x32x16_bf16 v[66:81], v[146:149], v[126:129], v[66:81]
	ds_read_b128 v[178:181], v225 offset:26656
	s_waitcnt lgkmcnt(7)
	v_mfma_f32_32x32x16_bf16 v[82:97], v[150:153], v[126:129], v[82:97]
	ds_read_b128 v[182:185], v225 offset:35360
	s_waitcnt lgkmcnt(7)
	v_mfma_f32_32x32x16_bf16 v[66:81], v[154:157], v[130:133], v[66:81]
	ds_read_b128 v[186:189], v225 offset:26688
	s_waitcnt lgkmcnt(7)
	v_mfma_f32_32x32x16_bf16 v[82:97], v[158:161], v[130:133], v[82:97]
	ds_read_b128 v[190:193], v225 offset:35392
	s_waitcnt lgkmcnt(7)
	v_mfma_f32_32x32x16_bf16 v[66:81], v[162:165], v[134:137], v[66:81]
	s_waitcnt lgkmcnt(6)
	v_mfma_f32_32x32x16_bf16 v[82:97], v[166:169], v[134:137], v[82:97]
	s_mov_b32 s41, 0
	s_cmp_lg_u32 s7, 0
	s_cbranch_scc1 .Lat_first_A2
.Lat_exp_A2:
	v_exp_f32_e32 v34, v34
	v_exp_f32_e32 v50, v50
	v_exp_f32_e32 v35, v35
	v_exp_f32_e32 v51, v51
	v_exp_f32_e32 v36, v36
	v_exp_f32_e32 v52, v52
	v_exp_f32_e32 v37, v37
	v_exp_f32_e32 v53, v53
	v_exp_f32_e32 v38, v38
	v_exp_f32_e32 v54, v54
	v_exp_f32_e32 v39, v39
	v_exp_f32_e32 v55, v55
	v_exp_f32_e32 v40, v40
	v_exp_f32_e32 v56, v56
	v_exp_f32_e32 v41, v41
	v_exp_f32_e32 v57, v57
	v_exp_f32_e32 v42, v42
	v_exp_f32_e32 v58, v58
	v_exp_f32_e32 v43, v43
	v_exp_f32_e32 v59, v59
	v_exp_f32_e32 v44, v44
	v_exp_f32_e32 v60, v60
	v_exp_f32_e32 v45, v45
	v_exp_f32_e32 v61, v61
	v_exp_f32_e32 v46, v46
	v_exp_f32_e32 v62, v62
	v_exp_f32_e32 v47, v47
	v_exp_f32_e32 v63, v63
	v_exp_f32_e32 v48, v48
	v_exp_f32_e32 v64, v64
	v_exp_f32_e32 v49, v49
	v_exp_f32_e32 v65, v65
	v_pk_add_f32 v[250:251], v[34:35], v[36:37]
	v_pk_add_f32 v[252:253], v[50:51], v[52:53]
	v_pk_add_f32 v[250:251], v[250:251], v[38:39]
	v_pk_add_f32 v[252:253], v[252:253], v[54:55]
	v_pk_add_f32 v[250:251], v[250:251], v[40:41]
	v_pk_add_f32 v[252:253], v[252:253], v[56:57]
	v_pk_add_f32 v[250:251], v[250:251], v[42:43]
	v_pk_add_f32 v[252:253], v[252:253], v[58:59]
	v_pk_add_f32 v[250:251], v[250:251], v[44:45]
	v_pk_add_f32 v[252:253], v[252:253], v[60:61]
	v_pk_add_f32 v[250:251], v[250:251], v[46:47]
	v_pk_add_f32 v[252:253], v[252:253], v[62:63]
	v_pk_add_f32 v[250:251], v[250:251], v[48:49]
	v_pk_add_f32 v[252:253], v[252:253], v[64:65]
	v_pk_add_f32 v[250:251], v[250:251], v[252:253]
	v_add_f32_e32 v1, v250, v251
.Lat_sum_A2:
	v_cmp_lt_f32_e32 vcc, s26, v1
	s_cbranch_vccnz .Lat_rare_A2
